# + m24: the h-row pass in the batch-0 scan_p1/sgu phase handles, per XCD, the rows that XCD owns (8 consecutive rows per wave); the batch-0 in-proj -> scan_p1/sgu barrier becomes XCD-local (no write-ba
# baseline (speedup 1.0000x reference)
; __device__ __forceinline__ float sq8(const f32x4& a, const f32x4& b) { return (a[0] * a[0] + a[1] * a[1]) + (a[2] * a[2] + a[3] * a[3]) + (b[0] * b[0] + b[1] * b[1]) + (b[2] * b[2] + b[3] * b[3]); }
; __device__ __forceinline__ void rows_r0(const float* xin, const float* g, bf16* H, int row0, int nrows, int wave, int lane) {
;     const int gw = blockIdx.x * 8 + wave, NGW = gridDim.x * 8;
;     f32x4 ga[2], gb[2];
; #pragma unroll
;     for (int j = 0; j < 2; ++j) ldrow8(g + 8 * lane + 512 * j, ga[j], gb[j]);
;     for (int m = gw; m < nrows; m += NGW) {
;         const float* xr = xin + (size_t)(row0 + m) * D + 8 * lane; f32x4 va[2], vb[2]; float s = 0.f;
; #pragma unroll
;         for (int j = 0; j < 2; ++j) { ldrow8(xr + 512 * j, va[j], vb[j]); s += sq8(va[j], vb[j]); }
;         const float r = rsqrtf(wave_sum(s) * (1.f / D) + EPS);
;         bf16* o = H + (size_t)m * D + 8 * lane;
; #pragma unroll
;         for (int j = 0; j < 2; ++j) st8bf(o + 512 * j, va[j] * r * ga[j], vb[j] * r * gb[j]);
;     }
; __global__ void __launch_bounds__(512, 2) mega(Args a) {
;     ...
;                 if (b == 0) rows_r0(xin, ka->in[2] + l * D, (bf16*)(ws + WS_H), TB, TB, wave, lane);
.LBB0_460:
	s_add_i32 s64, s64, 4
	s_cmp_lt_u32 s64, 11
	s_cbranch_scc0 .LBB0_464
	v_readlane_b32 s0, v255, 2
	s_and_b32 s6, s68, 7
	s_lshl_b32 s6, s6, 11
	s_lshr_b32 s98, s68, 3
	s_lshl_b32 s98, s98, 6
	s_add_i32 s6, s6, s98
	s_lshl_b32 s98, s69, 3
	s_add_i32 s6, s6, s98
	s_add_i32 s99, s6, 7
	s_cmpk_gt_i32 s6, 0x3fff
	s_cbranch_scc1 .LBB0_464
	s_load_dwordx2 s[0:1], s[66:67], 0x10
	s_lshl_b32 s8, s82, 10
	s_ashr_i32 s9, s8, 31
	s_lshl_b64 s[8:9], s[8:9], 2
	v_lshlrev_b32_e32 v18, 5, v211
	s_waitcnt lgkmcnt(0)
	s_add_u32 s0, s0, s8
	s_addc_u32 s1, s1, s9
	global_load_dwordx4 v[0:3], v18, s[0:1] offset:16
	global_load_dwordx4 v[4:7], v18, s[0:1]
	global_load_dwordx4 v[8:11], v18, s[0:1] offset:2064
	global_load_dwordx4 v[12:15], v18, s[0:1] offset:2048
	v_and_b32_e32 v17, 64, v254
	v_xor_b32_e32 v16, 16, v254
	v_add_u32_e32 v17, 64, v17
	v_cmp_lt_i32_e32 vcc, v16, v17
	s_ashr_i32 s7, s6, 31
	s_mov_b32 s8, 1
	v_cndmask_b32_e32 v16, v254, v16, vcc
	v_lshlrev_b32_e32 v20, 2, v16
	v_xor_b32_e32 v16, 32, v254
	s_lshl_b64 s[0:1], s[6:7], 11
	v_cmp_lt_i32_e32 vcc, v16, v17
	s_add_u32 s0, s30, s0
	v_lshlrev_b32_e32 v192, 4, v211
	v_cndmask_b32_e32 v16, v254, v16, vcc
	s_addc_u32 s1, s31, s1
	v_lshlrev_b32_e32 v21, 2, v16
	v_lshl_add_u64 v[16:17], s[0:1], 0, v[192:193]
	s_mov_b64 s[0:1], 0x2a00000
	v_lshl_add_u64 v[16:17], v[16:17], 0, s[0:1]
	s_add_i32 s0, s6, 0x4000
	s_ashr_i32 s9, s8, 31
	s_ashr_i32 s1, s0, 31
	s_lshl_b64 s[10:11], s[8:9], 11
	s_lshl_b64 s[0:1], s[0:1], 12
	v_readlane_b32 s12, v255, 16
	v_readlane_b32 s13, v255, 17
	s_add_u32 s0, s12, s0
	v_mov_b32_e32 v19, v193
	s_addc_u32 s1, s13, s1
	v_lshl_add_u64 v[18:19], s[0:1], 0, v[18:19]
	s_lshl_b64 s[12:13], s[8:9], 12
.LBB0_463:
	global_load_dwordx4 v[22:25], v[18:19], off offset:16
	global_load_dwordx4 v[26:29], v[18:19], off
	global_load_dwordx4 v[30:33], v[18:19], off offset:2064
	global_load_dwordx4 v[34:37], v[18:19], off offset:2048
	s_add_i32 s6, s6, s8
	v_lshl_add_u64 v[18:19], v[18:19], 0, s[12:13]
	s_cmp_gt_i32 s6, s99
	s_waitcnt vmcnt(0)
	v_mov_b32_e32 v40, v27
	v_mov_b32_e32 v38, v26
	v_mov_b32_e32 v41, v35
	v_mov_b32_e32 v39, v34
	v_pk_mul_f32 v[40:41], v[40:41], v[40:41]
	v_mov_b32_e32 v42, v29
	v_pk_fma_f32 v[38:39], v[38:39], v[38:39], v[40:41]
	v_mov_b32_e32 v40, v28
	v_mov_b32_e32 v41, v36
	v_pk_mul_f32 v[40:41], v[40:41], v[40:41]
	v_mov_b32_e32 v43, v37
	v_pk_fma_f32 v[40:41], v[42:43], v[42:43], v[40:41]
	v_mov_b32_e32 v42, v23
	v_mov_b32_e32 v43, v31
	v_pk_add_f32 v[38:39], v[38:39], v[40:41]
	v_mov_b32_e32 v40, v22
	v_mov_b32_e32 v41, v30
	v_pk_mul_f32 v[42:43], v[42:43], v[42:43]
	s_nop 0
	v_pk_fma_f32 v[40:41], v[40:41], v[40:41], v[42:43]
	v_mov_b32_e32 v42, v25
	v_pk_add_f32 v[38:39], v[38:39], v[40:41]
	v_mov_b32_e32 v40, v24
	v_mov_b32_e32 v41, v32
	v_pk_mul_f32 v[40:41], v[40:41], v[40:41]
	v_mov_b32_e32 v43, v33
	v_pk_fma_f32 v[40:41], v[42:43], v[42:43], v[40:41]
	s_nop 0
	v_pk_add_f32 v[38:39], v[40:41], v[38:39]
	s_nop 0
	v_add_f32_e32 v38, v38, v39
	s_nop 1
	v_add_f32_dpp v38, v38, v38 quad_perm:[1,0,3,2] row_mask:0xf bank_mask:0xf bound_ctrl:1
	s_nop 1
	v_add_f32_dpp v38, v38, v38 quad_perm:[2,3,0,1] row_mask:0xf bank_mask:0xf bound_ctrl:1
	s_nop 1
	v_add_f32_dpp v38, v38, v38 row_half_mirror row_mask:0xf bank_mask:0xf bound_ctrl:1
	s_nop 1
	v_add_f32_dpp v38, v38, v38 row_mirror row_mask:0xf bank_mask:0xf bound_ctrl:1
	ds_bpermute_b32 v39, v20, v38
	s_waitcnt lgkmcnt(0)
	v_add_f32_e32 v38, v38, v39
	ds_bpermute_b32 v39, v21, v38
	s_waitcnt lgkmcnt(0)
	v_add_f32_e32 v38, v38, v39
	v_fmamk_f32 v38, v38, 0x3a800000, v223
	v_cmp_gt_f32_e32 vcc, s24, v38
	v_mul_f32_e32 v39, 0x4b800000, v38
	s_nop 0
	v_cndmask_b32_e32 v38, v38, v39, vcc
	v_rsq_f32_e32 v38, v38
	s_nop 0
	v_mul_f32_e32 v39, 0x45800000, v38
	v_cndmask_b32_e32 v38, v38, v39, vcc
	v_pk_mul_f32 v[26:27], v[26:27], v[38:39] op_sel_hi:[1,0]
	v_pk_mul_f32 v[28:29], v[28:29], v[38:39] op_sel_hi:[1,0]
	v_pk_mul_f32 v[22:23], v[22:23], v[38:39] op_sel_hi:[1,0]
	v_pk_mul_f32 v[24:25], v[24:25], v[38:39] op_sel_hi:[1,0]
	v_pk_mul_f32 v[28:29], v[6:7], v[28:29]
	v_pk_mul_f32 v[26:27], v[4:5], v[26:27]
	v_pk_mul_f32 v[40:41], v[2:3], v[24:25]
	v_pk_mul_f32 v[24:25], v[0:1], v[22:23]
	v_cvt_pk_bf16_f32 v22, v26, v27
	v_cvt_pk_bf16_f32 v23, v28, v29
	v_cvt_pk_bf16_f32 v24, v24, v25
	v_cvt_pk_bf16_f32 v25, v40, v41
	global_store_dwordx4 v[16:17], v[22:25], off
	v_pk_mul_f32 v[26:27], v[30:31], v[38:39] op_sel_hi:[1,0]
	v_pk_mul_f32 v[28:29], v[32:33], v[38:39] op_sel_hi:[1,0]
	v_pk_mul_f32 v[22:23], v[34:35], v[38:39] op_sel_hi:[1,0]
	v_pk_mul_f32 v[24:25], v[36:37], v[38:39] op_sel_hi:[1,0]
	v_pk_mul_f32 v[22:23], v[12:13], v[22:23]
	v_pk_mul_f32 v[24:25], v[14:15], v[24:25]
	v_pk_mul_f32 v[28:29], v[10:11], v[28:29]
	v_pk_mul_f32 v[26:27], v[8:9], v[26:27]
	v_cvt_pk_bf16_f32 v22, v22, v23
	v_cvt_pk_bf16_f32 v23, v24, v25
	v_cvt_pk_bf16_f32 v24, v26, v27
	v_cvt_pk_bf16_f32 v25, v28, v29
	global_store_dwordx4 v[16:17], v[22:25], off offset:1024
	v_lshl_add_u64 v[16:17], v[16:17], 0, s[10:11]
	s_cbranch_scc0 .LBB0_463

; __device__ __forceinline__ unsigned xb_ld(unsigned* p)              { return __hip_atomic_load(p, __ATOMIC_RELAXED, __HIP_MEMORY_SCOPE_AGENT); }
; __device__ __forceinline__ unsigned xb_add(unsigned* p, unsigned v) { return __hip_atomic_fetch_add(p, v, __ATOMIC_RELAXED, __HIP_MEMORY_SCOPE_AGENT); }
; #define XB_SPIN(cond, bar) do { unsigned _sp = 0; while (cond) { __builtin_amdgcn_s_sleep(0); \
;     if ((++_sp & 255u) == 0u) { if (xb_ld(&(bar)[XB_TMO])) break; if (_sp > XB_SPIN_CAP) { atomicAdd(&(bar)[XB_TMO], 1u); break; } } } } while (0)
; __device__ __forceinline__ void xcd_barrier(const XcdBarrier& b) {
;     ...
;         const unsigned old = xb_add(&bar[XB_XSUB(b.x)], 1u);
;         const unsigned gen = old / nloc;
;         if (old + 1u == (gen + 1u) * nloc) {
;             __builtin_amdgcn_fence(__ATOMIC_RELEASE, "agent");
;             asm volatile("s_waitcnt vmcnt(0)" ::: "memory");
;             const unsigned og = xb_add(&bar[XB_TOP], 1u);
;             const unsigned tg = og / nx;
;             if (og + 1u == (tg + 1u) * nx) xb_add(&bar[XB_TOPGEN], 1u);
;             else XB_SPIN(xb_ld(&bar[XB_TOPGEN]) == tg, bar);
;             __builtin_amdgcn_fence(__ATOMIC_ACQUIRE, "agent");
;             xb_add(&bar[XB_XGEN(b.x)], 1u);
;             asm volatile("s_waitcnt vmcnt(0)" ::: "memory");
.LBB0_756:
	s_andn2_saveexec_b64 s[10:11], s[10:11]
	s_cbranch_execz .LBB0_776
	s_mov_b64 s[10:11], exec
	v_readlane_b32 s99, v255, 42
	s_cmp_ge_u32 s3, 18
	s_cselect_b32 s98, 18, 0
	s_sub_u32 s98, s3, s98
	s_cmp_eq_u32 s99, 0
	s_cbranch_scc1 .Lfull_l
	s_cmp_eq_u32 s98, 4
	s_cbranch_scc1 .Lnf_l4
	s_cmp_eq_u32 s98, 10
	s_cbranch_scc1 .Lnf_l4
	s_cmp_eq_u32 s98, 7
	s_cbranch_scc1 .Lnf_l4
	s_cmp_eq_u32 s98, 1
	s_cbranch_scc1 .Lnf_l4
	s_cmp_eq_u32 s98, 5
	s_cbranch_scc1 .Lnf_l
	s_cmp_eq_u32 s98, 6
	s_cbranch_scc1 .Lnf_l
	s_cmp_eq_u32 s98, 11
	s_cbranch_scc1 .Lnf_l
